# v64 + DSA bit search D (scalar prefix, carry-in counts, bit-plane popcount total, exact-256 early exit) + folded score scaling
# speedup vs baseline: 1.0073x; 1.0053x over previous
.LBB0_759:
	s_and_b64 vcc, exec, s[44:45]
	s_cbranch_vccz .LBB0_765
	s_and_b64 vcc, exec, s[60:61]
	s_cbranch_vccz .LBB0_766
	s_and_b64 vcc, exec, s[34:35]
	s_cbranch_vccz .LBB0_767
	s_mov_b32 s4, 31
	v_mov_b32_e32 v0, 0
	s_mov_b32 s64, 0
	s_movk_i32 s66, 0xff
.LBB0_763:
	s_lshl_b32 s5, 1, s4
	s_or_b32 s5, s5, s64
	s_add_i32 s4, s4, -1
	v_mov_b32_e32 v2, 0
	v_mov_b32_e32 v3, 0
	v_cmp_le_u32_e64 s[70:71], s5, v32
	v_cmp_le_u32_e64 s[72:73], s5, v33
	v_cmp_le_u32_e64 s[74:75], s5, v34
	v_cmp_le_u32_e64 s[76:77], s5, v35
	v_cmp_le_u32_e64 s[78:79], s5, v36
	v_cmp_le_u32_e64 s[80:81], s5, v37
	v_cmp_le_u32_e64 s[82:83], s5, v38
	v_cmp_le_u32_e64 s[84:85], s5, v39
	v_addc_co_u32_e64 v2, s[86:87], 0, v2, s[70:71]
	v_addc_co_u32_e64 v3, s[86:87], 0, v3, s[72:73]
	v_addc_co_u32_e64 v2, s[86:87], 0, v2, s[74:75]
	v_addc_co_u32_e64 v3, s[86:87], 0, v3, s[76:77]
	v_cmp_le_u32_e64 s[70:71], s5, v40
	v_cmp_le_u32_e64 s[72:73], s5, v41
	v_cmp_le_u32_e64 s[74:75], s5, v42
	v_cmp_le_u32_e64 s[76:77], s5, v43
	v_addc_co_u32_e64 v2, s[86:87], 0, v2, s[78:79]
	v_addc_co_u32_e64 v3, s[86:87], 0, v3, s[80:81]
	v_addc_co_u32_e64 v2, s[86:87], 0, v2, s[82:83]
	v_addc_co_u32_e64 v3, s[86:87], 0, v3, s[84:85]
	v_cmp_le_u32_e64 s[78:79], s5, v44
	v_cmp_le_u32_e64 s[80:81], s5, v45
	v_cmp_le_u32_e64 s[82:83], s5, v46
	v_cmp_le_u32_e64 s[84:85], s5, v47
	v_addc_co_u32_e64 v2, s[86:87], 0, v2, s[70:71]
	v_addc_co_u32_e64 v3, s[86:87], 0, v3, s[72:73]
	v_addc_co_u32_e64 v2, s[86:87], 0, v2, s[74:75]
	v_addc_co_u32_e64 v3, s[86:87], 0, v3, s[76:77]
	v_cmp_le_u32_e64 s[70:71], s5, v48
	v_cmp_le_u32_e64 s[72:73], s5, v49
	v_cmp_le_u32_e64 s[74:75], s5, v50
	v_cmp_le_u32_e64 s[76:77], s5, v51
	v_addc_co_u32_e64 v2, s[86:87], 0, v2, s[78:79]
	v_addc_co_u32_e64 v3, s[86:87], 0, v3, s[80:81]
	v_addc_co_u32_e64 v2, s[86:87], 0, v2, s[82:83]
	v_addc_co_u32_e64 v3, s[86:87], 0, v3, s[84:85]
	v_cmp_le_u32_e64 s[78:79], s5, v52
	v_cmp_le_u32_e64 s[80:81], s5, v53
	v_cmp_le_u32_e64 s[82:83], s5, v54
	v_cmp_le_u32_e64 s[84:85], s5, v55
	v_addc_co_u32_e64 v2, s[86:87], 0, v2, s[70:71]
	v_addc_co_u32_e64 v3, s[86:87], 0, v3, s[72:73]
	v_addc_co_u32_e64 v2, s[86:87], 0, v2, s[74:75]
	v_addc_co_u32_e64 v3, s[86:87], 0, v3, s[76:77]
	v_cmp_le_u32_e64 s[70:71], s5, v56
	v_cmp_le_u32_e64 s[72:73], s5, v57
	v_cmp_le_u32_e64 s[74:75], s5, v58
	v_cmp_le_u32_e64 s[76:77], s5, v59
	v_addc_co_u32_e64 v2, s[86:87], 0, v2, s[78:79]
	v_addc_co_u32_e64 v3, s[86:87], 0, v3, s[80:81]
	v_addc_co_u32_e64 v2, s[86:87], 0, v2, s[82:83]
	v_addc_co_u32_e64 v3, s[86:87], 0, v3, s[84:85]
	v_cmp_le_u32_e64 s[78:79], s5, v60
	v_cmp_le_u32_e64 s[80:81], s5, v61
	v_cmp_le_u32_e64 s[82:83], s5, v62
	v_cmp_le_u32_e64 s[84:85], s5, v63
	v_addc_co_u32_e64 v2, s[86:87], 0, v2, s[70:71]
	v_addc_co_u32_e64 v3, s[86:87], 0, v3, s[72:73]
	v_addc_co_u32_e64 v2, s[86:87], 0, v2, s[74:75]
	v_addc_co_u32_e64 v3, s[86:87], 0, v3, s[76:77]
	v_addc_co_u32_e64 v2, s[86:87], 0, v2, s[78:79]
	v_addc_co_u32_e64 v3, s[86:87], 0, v3, s[80:81]
	v_addc_co_u32_e64 v2, s[86:87], 0, v2, s[82:83]
	v_addc_co_u32_e64 v3, s[86:87], 0, v3, s[84:85]
	v_add_u32_e32 v2, v2, v3
	v_and_b32_e32 v4, 1, v2
	v_and_b32_e32 v5, 2, v2
	v_and_b32_e32 v6, 4, v2
	v_and_b32_e32 v7, 8, v2
	v_and_b32_e32 v8, 16, v2
	v_and_b32_e32 v9, 32, v2
	v_cmp_ne_u32_e64 s[70:71], 0, v4
	v_cmp_ne_u32_e64 s[72:73], 0, v5
	v_cmp_ne_u32_e64 s[74:75], 0, v6
	v_cmp_ne_u32_e64 s[76:77], 0, v7
	v_cmp_ne_u32_e64 s[78:79], 0, v8
	v_cmp_ne_u32_e64 s[80:81], 0, v9
	s_bcnt1_i32_b64 s7, s[80:81]
	s_bcnt1_i32_b64 s6, s[78:79]
	s_lshl1_add_u32 s7, s7, s6
	s_bcnt1_i32_b64 s6, s[76:77]
	s_lshl1_add_u32 s7, s7, s6
	s_bcnt1_i32_b64 s6, s[74:75]
	s_lshl1_add_u32 s7, s7, s6
	s_bcnt1_i32_b64 s6, s[72:73]
	s_lshl1_add_u32 s7, s7, s6
	s_bcnt1_i32_b64 s6, s[70:71]
	s_lshl1_add_u32 s7, s7, s6
	s_cmp_eq_u32 s7, 0x100
	s_cbranch_scc0 .Lbs_ne0
	s_add_i32 s64, s5, -1
	s_mov_b32 s4, -1
	s_branch .Lbs_fin0
.Lbs_ne0:
	s_cmp_gt_u32 s7, 0xff
	s_cselect_b32 s64, s5, s64
.Lbs_fin0:
	v_mov_b32_e32 v0, s64
	s_cmp_lg_u32 s4, -1
	s_cbranch_scc1 .LBB0_763
	s_branch .LBB0_770

.LBB0_767:
	s_cbranch_execz .LBB0_770
	s_mov_b32 s4, 31
	v_mov_b32_e32 v0, 0
	s_mov_b32 s64, 0
	s_movk_i32 s66, 0xff
.LBB0_769:
	s_lshl_b32 s5, 1, s4
	s_or_b32 s5, s5, s64
	s_add_i32 s4, s4, -1
	v_mov_b32_e32 v2, 0
	v_mov_b32_e32 v3, 0
	v_cmp_le_u32_e64 s[70:71], s5, v32
	v_cmp_le_u32_e64 s[72:73], s5, v33
	v_cmp_le_u32_e64 s[74:75], s5, v34
	v_cmp_le_u32_e64 s[76:77], s5, v35
	v_cmp_le_u32_e64 s[78:79], s5, v36
	v_cmp_le_u32_e64 s[80:81], s5, v37
	v_cmp_le_u32_e64 s[82:83], s5, v38
	v_cmp_le_u32_e64 s[84:85], s5, v39
	v_addc_co_u32_e64 v2, s[86:87], 0, v2, s[70:71]
	v_addc_co_u32_e64 v3, s[86:87], 0, v3, s[72:73]
	v_addc_co_u32_e64 v2, s[86:87], 0, v2, s[74:75]
	v_addc_co_u32_e64 v3, s[86:87], 0, v3, s[76:77]
	v_cmp_le_u32_e64 s[70:71], s5, v40
	v_cmp_le_u32_e64 s[72:73], s5, v41
	v_cmp_le_u32_e64 s[74:75], s5, v42
	v_cmp_le_u32_e64 s[76:77], s5, v43
	v_addc_co_u32_e64 v2, s[86:87], 0, v2, s[78:79]
	v_addc_co_u32_e64 v3, s[86:87], 0, v3, s[80:81]
	v_addc_co_u32_e64 v2, s[86:87], 0, v2, s[82:83]
	v_addc_co_u32_e64 v3, s[86:87], 0, v3, s[84:85]
	v_cmp_le_u32_e64 s[78:79], s5, v44
	v_cmp_le_u32_e64 s[80:81], s5, v45
	v_cmp_le_u32_e64 s[82:83], s5, v46
	v_cmp_le_u32_e64 s[84:85], s5, v47
	v_addc_co_u32_e64 v2, s[86:87], 0, v2, s[70:71]
	v_addc_co_u32_e64 v3, s[86:87], 0, v3, s[72:73]
	v_addc_co_u32_e64 v2, s[86:87], 0, v2, s[74:75]
	v_addc_co_u32_e64 v3, s[86:87], 0, v3, s[76:77]
	v_cmp_le_u32_e64 s[70:71], s5, v48
	v_cmp_le_u32_e64 s[72:73], s5, v49
	v_cmp_le_u32_e64 s[74:75], s5, v50
	v_cmp_le_u32_e64 s[76:77], s5, v51
	v_addc_co_u32_e64 v2, s[86:87], 0, v2, s[78:79]
	v_addc_co_u32_e64 v3, s[86:87], 0, v3, s[80:81]
	v_addc_co_u32_e64 v2, s[86:87], 0, v2, s[82:83]
	v_addc_co_u32_e64 v3, s[86:87], 0, v3, s[84:85]
	v_cmp_le_u32_e64 s[78:79], s5, v52
	v_cmp_le_u32_e64 s[80:81], s5, v53
	v_cmp_le_u32_e64 s[82:83], s5, v54
	v_cmp_le_u32_e64 s[84:85], s5, v55
	v_addc_co_u32_e64 v2, s[86:87], 0, v2, s[70:71]
	v_addc_co_u32_e64 v3, s[86:87], 0, v3, s[72:73]
	v_addc_co_u32_e64 v2, s[86:87], 0, v2, s[74:75]
	v_addc_co_u32_e64 v3, s[86:87], 0, v3, s[76:77]
	v_addc_co_u32_e64 v2, s[86:87], 0, v2, s[78:79]
	v_addc_co_u32_e64 v3, s[86:87], 0, v3, s[80:81]
	v_addc_co_u32_e64 v2, s[86:87], 0, v2, s[82:83]
	v_addc_co_u32_e64 v3, s[86:87], 0, v3, s[84:85]
	v_add_u32_e32 v2, v2, v3
	v_and_b32_e32 v4, 1, v2
	v_and_b32_e32 v5, 2, v2
	v_and_b32_e32 v6, 4, v2
	v_and_b32_e32 v7, 8, v2
	v_and_b32_e32 v8, 16, v2
	v_and_b32_e32 v9, 32, v2
	v_cmp_ne_u32_e64 s[70:71], 0, v4
	v_cmp_ne_u32_e64 s[72:73], 0, v5
	v_cmp_ne_u32_e64 s[74:75], 0, v6
	v_cmp_ne_u32_e64 s[76:77], 0, v7
	v_cmp_ne_u32_e64 s[78:79], 0, v8
	v_cmp_ne_u32_e64 s[80:81], 0, v9
	s_bcnt1_i32_b64 s7, s[80:81]
	s_bcnt1_i32_b64 s6, s[78:79]
	s_lshl1_add_u32 s7, s7, s6
	s_bcnt1_i32_b64 s6, s[76:77]
	s_lshl1_add_u32 s7, s7, s6
	s_bcnt1_i32_b64 s6, s[74:75]
	s_lshl1_add_u32 s7, s7, s6
	s_bcnt1_i32_b64 s6, s[72:73]
	s_lshl1_add_u32 s7, s7, s6
	s_bcnt1_i32_b64 s6, s[70:71]
	s_lshl1_add_u32 s7, s7, s6
	s_cmp_eq_u32 s7, 0x100
	s_cbranch_scc0 .Lbs_ne1
	s_add_i32 s64, s5, -1
	s_mov_b32 s4, -1
	s_branch .Lbs_fin1

.Lbs_fin1:
	v_mov_b32_e32 v0, s64
	s_cmp_eq_u32 s4, -1
	s_cbranch_scc0 .LBB0_769

.LBB0_771:
	s_mov_b32 s4, 31
	v_mov_b32_e32 v0, 0
	s_mov_b32 s64, 0
	s_movk_i32 s66, 0xff
.LBB0_772:
	s_lshl_b32 s5, 1, s4
	s_or_b32 s5, s5, s64
	s_add_i32 s4, s4, -1
	v_mov_b32_e32 v2, 0
	v_mov_b32_e32 v3, 0
	v_cmp_le_u32_e64 s[70:71], s5, v32
	v_cmp_le_u32_e64 s[72:73], s5, v33
	v_cmp_le_u32_e64 s[74:75], s5, v34
	v_cmp_le_u32_e64 s[76:77], s5, v35
	v_cmp_le_u32_e64 s[78:79], s5, v36
	v_cmp_le_u32_e64 s[80:81], s5, v37
	v_cmp_le_u32_e64 s[82:83], s5, v38
	v_cmp_le_u32_e64 s[84:85], s5, v39
	v_addc_co_u32_e64 v2, s[86:87], 0, v2, s[70:71]
	v_addc_co_u32_e64 v3, s[86:87], 0, v3, s[72:73]
	v_addc_co_u32_e64 v2, s[86:87], 0, v2, s[74:75]
	v_addc_co_u32_e64 v3, s[86:87], 0, v3, s[76:77]
	v_cmp_le_u32_e64 s[70:71], s5, v40
	v_cmp_le_u32_e64 s[72:73], s5, v41
	v_cmp_le_u32_e64 s[74:75], s5, v42
	v_cmp_le_u32_e64 s[76:77], s5, v43
	v_addc_co_u32_e64 v2, s[86:87], 0, v2, s[78:79]
	v_addc_co_u32_e64 v3, s[86:87], 0, v3, s[80:81]
	v_addc_co_u32_e64 v2, s[86:87], 0, v2, s[82:83]
	v_addc_co_u32_e64 v3, s[86:87], 0, v3, s[84:85]
	v_cmp_le_u32_e64 s[78:79], s5, v44
	v_cmp_le_u32_e64 s[80:81], s5, v45
	v_cmp_le_u32_e64 s[82:83], s5, v46
	v_cmp_le_u32_e64 s[84:85], s5, v47
	v_addc_co_u32_e64 v2, s[86:87], 0, v2, s[70:71]
	v_addc_co_u32_e64 v3, s[86:87], 0, v3, s[72:73]
	v_addc_co_u32_e64 v2, s[86:87], 0, v2, s[74:75]
	v_addc_co_u32_e64 v3, s[86:87], 0, v3, s[76:77]
	v_addc_co_u32_e64 v2, s[86:87], 0, v2, s[78:79]
	v_addc_co_u32_e64 v3, s[86:87], 0, v3, s[80:81]
	v_addc_co_u32_e64 v2, s[86:87], 0, v2, s[82:83]
	v_addc_co_u32_e64 v3, s[86:87], 0, v3, s[84:85]
	v_add_u32_e32 v2, v2, v3
	v_and_b32_e32 v4, 1, v2
	v_and_b32_e32 v5, 2, v2
	v_and_b32_e32 v6, 4, v2
	v_and_b32_e32 v7, 8, v2
	v_and_b32_e32 v8, 16, v2
	v_and_b32_e32 v9, 32, v2
	v_cmp_ne_u32_e64 s[70:71], 0, v4
	v_cmp_ne_u32_e64 s[72:73], 0, v5
	v_cmp_ne_u32_e64 s[74:75], 0, v6
	v_cmp_ne_u32_e64 s[76:77], 0, v7
	v_cmp_ne_u32_e64 s[78:79], 0, v8
	v_cmp_ne_u32_e64 s[80:81], 0, v9
	s_bcnt1_i32_b64 s7, s[80:81]
	s_bcnt1_i32_b64 s6, s[78:79]
	s_lshl1_add_u32 s7, s7, s6
	s_bcnt1_i32_b64 s6, s[76:77]
	s_lshl1_add_u32 s7, s7, s6
	s_bcnt1_i32_b64 s6, s[74:75]
	s_lshl1_add_u32 s7, s7, s6
	s_bcnt1_i32_b64 s6, s[72:73]
	s_lshl1_add_u32 s7, s7, s6
	s_bcnt1_i32_b64 s6, s[70:71]
	s_lshl1_add_u32 s7, s7, s6
	s_cmp_eq_u32 s7, 0x100
	s_cbranch_scc0 .Lbs_ne2
	s_add_i32 s64, s5, -1
	s_mov_b32 s4, -1
	s_branch .Lbs_fin2

.LBB0_775:
	s_lshl_b32 s5, 1, s4
	s_or_b32 s5, s5, s64
	s_add_i32 s4, s4, -1
	v_mov_b32_e32 v2, 0
	v_mov_b32_e32 v3, 0
	v_cmp_le_u32_e64 s[70:71], s5, v32
	v_cmp_le_u32_e64 s[72:73], s5, v33
	v_cmp_le_u32_e64 s[74:75], s5, v34
	v_cmp_le_u32_e64 s[76:77], s5, v35
	v_cmp_le_u32_e64 s[78:79], s5, v36
	v_cmp_le_u32_e64 s[80:81], s5, v37
	v_cmp_le_u32_e64 s[82:83], s5, v38
	v_cmp_le_u32_e64 s[84:85], s5, v39
	v_addc_co_u32_e64 v2, s[86:87], 0, v2, s[70:71]
	v_addc_co_u32_e64 v3, s[86:87], 0, v3, s[72:73]
	v_addc_co_u32_e64 v2, s[86:87], 0, v2, s[74:75]
	v_addc_co_u32_e64 v3, s[86:87], 0, v3, s[76:77]
	v_addc_co_u32_e64 v2, s[86:87], 0, v2, s[78:79]
	v_addc_co_u32_e64 v3, s[86:87], 0, v3, s[80:81]
	v_addc_co_u32_e64 v2, s[86:87], 0, v2, s[82:83]
	v_addc_co_u32_e64 v3, s[86:87], 0, v3, s[84:85]
	v_add_u32_e32 v2, v2, v3
	v_and_b32_e32 v4, 1, v2
	v_and_b32_e32 v5, 2, v2
	v_and_b32_e32 v6, 4, v2
	v_and_b32_e32 v7, 8, v2
	v_and_b32_e32 v8, 16, v2
	v_and_b32_e32 v9, 32, v2
	v_cmp_ne_u32_e64 s[70:71], 0, v4
	v_cmp_ne_u32_e64 s[72:73], 0, v5
	v_cmp_ne_u32_e64 s[74:75], 0, v6
	v_cmp_ne_u32_e64 s[76:77], 0, v7
	v_cmp_ne_u32_e64 s[78:79], 0, v8
	v_cmp_ne_u32_e64 s[80:81], 0, v9
	s_bcnt1_i32_b64 s7, s[80:81]
	s_bcnt1_i32_b64 s6, s[78:79]
	s_lshl1_add_u32 s7, s7, s6
	s_bcnt1_i32_b64 s6, s[76:77]
	s_lshl1_add_u32 s7, s7, s6
	s_bcnt1_i32_b64 s6, s[74:75]
	s_lshl1_add_u32 s7, s7, s6
	s_bcnt1_i32_b64 s6, s[72:73]
	s_lshl1_add_u32 s7, s7, s6
	s_bcnt1_i32_b64 s6, s[70:71]
	s_lshl1_add_u32 s7, s7, s6
	s_cmp_eq_u32 s7, 0x100
	s_cbranch_scc0 .Lbs_ne3
	s_add_i32 s64, s5, -1
	s_mov_b32 s4, -1
	s_branch .Lbs_fin3
